# grid barrier: non-last workgroups poll the top-level generation word directly (one fewer dependent round trip), per-XCD forward removed
# speedup vs baseline: 1.0345x; 1.0033x over previous
; __device__ __forceinline__ unsigned xb_ld(unsigned* p)              { return __hip_atomic_load(p, __ATOMIC_RELAXED, __HIP_MEMORY_SCOPE_AGENT); }
; __device__ __forceinline__ unsigned xb_add(unsigned* p, unsigned v) { return __hip_atomic_fetch_add(p, v, __ATOMIC_RELAXED, __HIP_MEMORY_SCOPE_AGENT); }
; #define XB_SPIN(cond, bar) do { unsigned _sp = 0; while (cond) { __builtin_amdgcn_s_sleep(1); \
;     if ((++_sp & 255u) == 0u) { if (xb_ld(&(bar)[XB_TMO])) break; if (_sp > XB_SPIN_CAP) { atomicAdd(&(bar)[XB_TMO], 1u); break; } } } } while (0)
; __device__ __forceinline__ void xcd_barrier(const XcdBarrier& b) {
;     ...
;         const unsigned old = xb_add(&bar[XB_XSUB(b.x)], 1u);
;         const unsigned gen = old / nloc;
;         if (old + 1u == (gen + 1u) * nloc) {
;             __builtin_amdgcn_fence(__ATOMIC_RELEASE, "agent");
;             asm volatile("s_waitcnt vmcnt(0)" ::: "memory");
;             const unsigned og = xb_add(&bar[XB_TOP], 1u);
;             const unsigned tg = og / nx;
;             if (og + 1u == (tg + 1u) * nx) xb_add(&bar[XB_TOPGEN], 1u);
;             else XB_SPIN(xb_ld(&bar[XB_TOPGEN]) == tg, bar);
;             __builtin_amdgcn_fence(__ATOMIC_ACQUIRE, "agent");
;             xb_add(&bar[XB_XGEN(b.x)], 1u);
;             asm volatile("s_waitcnt vmcnt(0)" ::: "memory");
;         } else {
;             XB_SPIN(xb_ld(&bar[XB_XGEN(b.x)]) == gen, bar);
.LBB0_49:
	s_or_b64 exec, exec, s[14:15]
	v_cvt_f32_u32_e32 v5, v3
	s_waitcnt vmcnt(0)
	v_readfirstlane_b32 s3, v4
	v_sub_u32_e32 v4, 0, v3
	v_rcp_iflag_f32_e32 v5, v5
	v_add_u32_e32 v6, s3, v2
	v_mul_f32_e32 v5, 0x4f7ffffe, v5
	v_cvt_u32_f32_e32 v5, v5
	v_mul_lo_u32 v2, v4, v5
	v_mul_hi_u32 v2, v5, v2
	v_add_u32_e32 v2, v5, v2
	v_mul_hi_u32 v2, v6, v2
	v_mul_lo_u32 v4, v2, v3
	v_sub_u32_e32 v4, v6, v4
	v_add_u32_e32 v5, 1, v2
	v_cmp_ge_u32_e32 vcc, v4, v3
	s_nop 1
	v_cndmask_b32_e32 v2, v2, v5, vcc
	v_sub_u32_e32 v5, v4, v3
	v_cndmask_b32_e32 v4, v4, v5, vcc
	v_add_u32_e32 v5, 1, v2
	v_cmp_ge_u32_e32 vcc, v4, v3
	v_add_u32_e32 v4, 1, v6
	s_nop 0
	v_cndmask_b32_e32 v2, v2, v5, vcc
	v_mul_lo_u32 v5, v3, v2
	v_add_u32_e32 v3, v5, v3
	v_cmp_ne_u32_e32 vcc, v4, v3
	s_and_saveexec_b64 s[12:13], vcc
	s_xor_b64 s[12:13], exec, s[12:13]
	s_cbranch_execz .LBB0_63
	s_waitcnt lgkmcnt(0)
	v_mov_b32_e32 v1, 0x3500
	global_load_dword v1, v1, s[74:75] sc1
	s_add_u32 s18, s74, 0x3500
	s_addc_u32 s19, s75, 0
	s_waitcnt vmcnt(0)
	v_cmp_eq_u32_e32 vcc, v1, v2
	s_and_saveexec_b64 s[14:15], vcc
	s_cbranch_execz .LBB0_62
	s_add_u32 s16, s70, 0xc80200
	s_addc_u32 s17, s71, 0
	s_mov_b32 s3, 1
	s_mov_b64 s[20:21], 0
	v_mov_b32_e32 v1, 0
	s_branch .LBB0_53

; __device__ __forceinline__ unsigned xb_add(unsigned* p, unsigned v) { return __hip_atomic_fetch_add(p, v, __ATOMIC_RELAXED, __HIP_MEMORY_SCOPE_AGENT); }
; __device__ __forceinline__ void xcd_barrier(const XcdBarrier& b) {
;     ...
;             __builtin_amdgcn_fence(__ATOMIC_ACQUIRE, "agent");
;             xb_add(&bar[XB_XGEN(b.x)], 1u);
;             asm volatile("s_waitcnt vmcnt(0)" ::: "memory");
.LBB0_80:
	s_or_b64 exec, exec, s[12:13]
	s_mov_b64 s[12:13], exec
	v_mbcnt_lo_u32_b32 v1, s12, 0
	v_mbcnt_hi_u32_b32 v1, s13, v1
	v_cmp_eq_u32_e32 vcc, 0, v1
	s_waitcnt vmcnt(0)
	buffer_inv sc1
	s_and_saveexec_b64 s[14:15], vcc
	s_cbranch_execz .LBB0_82
	s_bcnt1_i32_b64 s3, s[12:13]
	v_mov_b32_e32 v1, 0x2000
	v_mov_b32_e32 v2, s3
.LBB0_82:
	s_or_b64 exec, exec, s[14:15]
	s_waitcnt vmcnt(0)

; __device__ __forceinline__ unsigned xb_add(unsigned* p, unsigned v) { return __hip_atomic_fetch_add(p, v, __ATOMIC_RELAXED, __HIP_MEMORY_SCOPE_AGENT); }
; __device__ __forceinline__ void xcd_barrier(const XcdBarrier& b) {
;     ...
;             __builtin_amdgcn_fence(__ATOMIC_ACQUIRE, "agent");
;             xb_add(&bar[XB_XGEN(b.x)], 1u);
;             asm volatile("s_waitcnt vmcnt(0)" ::: "memory");
.LBB0_154:
	s_or_b64 exec, exec, s[12:13]
	s_mov_b64 s[12:13], exec
	v_mbcnt_lo_u32_b32 v1, s12, 0
	v_mbcnt_hi_u32_b32 v1, s13, v1
	v_cmp_eq_u32_e32 vcc, 0, v1
	s_waitcnt vmcnt(0)
	buffer_inv sc1
	s_and_saveexec_b64 s[14:15], vcc
	s_cbranch_execz .LBB0_156
	s_bcnt1_i32_b64 s3, s[12:13]
	v_mov_b32_e32 v1, 0x2000
	v_mov_b32_e32 v2, s3
.LBB0_156:
	s_or_b64 exec, exec, s[14:15]
	s_waitcnt vmcnt(0)

; __device__ __forceinline__ unsigned xb_add(unsigned* p, unsigned v) { return __hip_atomic_fetch_add(p, v, __ATOMIC_RELAXED, __HIP_MEMORY_SCOPE_AGENT); }
; __device__ __forceinline__ void xcd_barrier(const XcdBarrier& b) {
;     ...
;             __builtin_amdgcn_fence(__ATOMIC_ACQUIRE, "agent");
;             xb_add(&bar[XB_XGEN(b.x)], 1u);
;             asm volatile("s_waitcnt vmcnt(0)" ::: "memory");
.LBB0_252:
	s_or_b64 exec, exec, s[12:13]
	s_mov_b64 s[12:13], exec
	v_mbcnt_lo_u32_b32 v1, s12, 0
	v_mbcnt_hi_u32_b32 v1, s13, v1
	v_cmp_eq_u32_e32 vcc, 0, v1
	s_waitcnt vmcnt(0)
	buffer_inv sc1
	s_and_saveexec_b64 s[14:15], vcc
	s_cbranch_execz .LBB0_254
	s_bcnt1_i32_b64 s3, s[12:13]
	v_mov_b32_e32 v1, 0x2000
	v_mov_b32_e32 v2, s3
.LBB0_254:
	s_or_b64 exec, exec, s[14:15]
	s_waitcnt vmcnt(0)

; __device__ __forceinline__ unsigned xb_add(unsigned* p, unsigned v) { return __hip_atomic_fetch_add(p, v, __ATOMIC_RELAXED, __HIP_MEMORY_SCOPE_AGENT); }
; __device__ __forceinline__ void xcd_barrier(const XcdBarrier& b) {
;     ...
;             __builtin_amdgcn_fence(__ATOMIC_ACQUIRE, "agent");
;             xb_add(&bar[XB_XGEN(b.x)], 1u);
;             asm volatile("s_waitcnt vmcnt(0)" ::: "memory");
.LBB0_358:
	s_or_b64 exec, exec, s[12:13]
	s_mov_b64 s[12:13], exec
	v_mbcnt_lo_u32_b32 v1, s12, 0
	v_mbcnt_hi_u32_b32 v1, s13, v1
	v_cmp_eq_u32_e32 vcc, 0, v1
	s_waitcnt vmcnt(0)
	buffer_inv sc1
	s_and_saveexec_b64 s[14:15], vcc
	s_cbranch_execz .LBB0_360
	s_bcnt1_i32_b64 s3, s[12:13]
	v_mov_b32_e32 v1, 0x2000
	v_mov_b32_e32 v2, s3
.LBB0_360:
	s_or_b64 exec, exec, s[14:15]
	s_waitcnt vmcnt(0)

; __device__ __forceinline__ unsigned xb_add(unsigned* p, unsigned v) { return __hip_atomic_fetch_add(p, v, __ATOMIC_RELAXED, __HIP_MEMORY_SCOPE_AGENT); }
; __device__ __forceinline__ void xcd_barrier(const XcdBarrier& b) {
;     ...
;             __builtin_amdgcn_fence(__ATOMIC_ACQUIRE, "agent");
;             xb_add(&bar[XB_XGEN(b.x)], 1u);
;             asm volatile("s_waitcnt vmcnt(0)" ::: "memory");
.LBB0_428:
	s_or_b64 exec, exec, s[12:13]
	s_mov_b64 s[12:13], exec
	v_mbcnt_lo_u32_b32 v1, s12, 0
	v_mbcnt_hi_u32_b32 v1, s13, v1
	v_cmp_eq_u32_e32 vcc, 0, v1
	s_waitcnt vmcnt(0)
	buffer_inv sc1
	s_and_saveexec_b64 s[14:15], vcc
	s_cbranch_execz .LBB0_430
	s_bcnt1_i32_b64 s3, s[12:13]
	v_mov_b32_e32 v1, 0x2000
	v_mov_b32_e32 v2, s3
.LBB0_430:
	s_or_b64 exec, exec, s[14:15]
	s_waitcnt vmcnt(0)

; __device__ __forceinline__ unsigned xb_ld(unsigned* p)              { return __hip_atomic_load(p, __ATOMIC_RELAXED, __HIP_MEMORY_SCOPE_AGENT); }
; __device__ __forceinline__ unsigned xb_add(unsigned* p, unsigned v) { return __hip_atomic_fetch_add(p, v, __ATOMIC_RELAXED, __HIP_MEMORY_SCOPE_AGENT); }
; #define XB_SPIN(cond, bar) do { unsigned _sp = 0; while (cond) { __builtin_amdgcn_s_sleep(1); \
;     if ((++_sp & 255u) == 0u) { if (xb_ld(&(bar)[XB_TMO])) break; if (_sp > XB_SPIN_CAP) { atomicAdd(&(bar)[XB_TMO], 1u); break; } } } } while (0)
; __device__ __forceinline__ void xcd_barrier(const XcdBarrier& b) {
;     ...
;         const unsigned old = xb_add(&bar[XB_XSUB(b.x)], 1u);
;         const unsigned gen = old / nloc;
;         if (old + 1u == (gen + 1u) * nloc) {
;             __builtin_amdgcn_fence(__ATOMIC_RELEASE, "agent");
;             asm volatile("s_waitcnt vmcnt(0)" ::: "memory");
;             const unsigned og = xb_add(&bar[XB_TOP], 1u);
;             const unsigned tg = og / nx;
;             if (og + 1u == (tg + 1u) * nx) xb_add(&bar[XB_TOPGEN], 1u);
;             else XB_SPIN(xb_ld(&bar[XB_TOPGEN]) == tg, bar);
;             __builtin_amdgcn_fence(__ATOMIC_ACQUIRE, "agent");
;             xb_add(&bar[XB_XGEN(b.x)], 1u);
;             asm volatile("s_waitcnt vmcnt(0)" ::: "memory");
;         } else {
;             XB_SPIN(xb_ld(&bar[XB_XGEN(b.x)]) == gen, bar);
.LBB0_474:
	s_or_b64 exec, exec, s[12:13]
	v_cvt_f32_u32_e32 v5, v3
	s_waitcnt vmcnt(0)
	v_readfirstlane_b32 s3, v4
	v_sub_u32_e32 v4, 0, v3
	v_rcp_iflag_f32_e32 v5, v5
	v_add_u32_e32 v6, s3, v2
	v_mul_f32_e32 v5, 0x4f7ffffe, v5
	v_cvt_u32_f32_e32 v5, v5
	v_mul_lo_u32 v2, v4, v5
	v_mul_hi_u32 v2, v5, v2
	v_add_u32_e32 v2, v5, v2
	v_mul_hi_u32 v2, v6, v2
	v_mul_lo_u32 v4, v2, v3
	v_sub_u32_e32 v4, v6, v4
	v_add_u32_e32 v5, 1, v2
	v_cmp_ge_u32_e32 vcc, v4, v3
	s_nop 1
	v_cndmask_b32_e32 v2, v2, v5, vcc
	v_sub_u32_e32 v5, v4, v3
	v_cndmask_b32_e32 v4, v4, v5, vcc
	v_add_u32_e32 v5, 1, v2
	v_cmp_ge_u32_e32 vcc, v4, v3
	v_add_u32_e32 v4, 1, v6
	s_nop 0
	v_cndmask_b32_e32 v2, v2, v5, vcc
	v_mul_lo_u32 v5, v3, v2
	v_add_u32_e32 v3, v5, v3
	v_cmp_ne_u32_e32 vcc, v4, v3
	s_and_saveexec_b64 s[10:11], vcc
	s_xor_b64 s[10:11], exec, s[10:11]
	s_cbranch_execz .LBB0_488
	s_waitcnt lgkmcnt(0)
	v_mov_b32_e32 v1, 0x3500
	global_load_dword v1, v1, s[74:75] sc1
	s_add_u32 s16, s74, 0x3500
	s_addc_u32 s17, s75, 0
	s_waitcnt vmcnt(0)
	v_cmp_eq_u32_e32 vcc, v1, v2
	s_and_saveexec_b64 s[12:13], vcc
	s_cbranch_execz .LBB0_487
	s_add_u32 s14, s70, 0xc80200
	s_addc_u32 s15, s71, 0
	s_mov_b32 s3, 1
	s_mov_b64 s[18:19], 0
	v_mov_b32_e32 v1, 0
	s_branch .LBB0_478

; __device__ __forceinline__ unsigned xb_add(unsigned* p, unsigned v) { return __hip_atomic_fetch_add(p, v, __ATOMIC_RELAXED, __HIP_MEMORY_SCOPE_AGENT); }
; __device__ __forceinline__ void xcd_barrier(const XcdBarrier& b) {
;     ...
;             __builtin_amdgcn_fence(__ATOMIC_ACQUIRE, "agent");
;             xb_add(&bar[XB_XGEN(b.x)], 1u);
;             asm volatile("s_waitcnt vmcnt(0)" ::: "memory");
.LBB0_505:
	s_or_b64 exec, exec, s[10:11]
	s_mov_b64 s[10:11], exec
	v_mbcnt_lo_u32_b32 v1, s10, 0
	v_mbcnt_hi_u32_b32 v1, s11, v1
	v_cmp_eq_u32_e32 vcc, 0, v1
	s_waitcnt vmcnt(0)
	buffer_inv sc1
	s_and_saveexec_b64 s[12:13], vcc
	s_cbranch_execz .LBB0_507
	s_bcnt1_i32_b64 s3, s[10:11]
	v_mov_b32_e32 v1, 0x2000
	v_mov_b32_e32 v2, s3
.LBB0_507:
	s_or_b64 exec, exec, s[12:13]
	s_waitcnt vmcnt(0)
